# baseline (speedup 1.0000x reference)
; #define LAS __attribute__((address_space(3)))
; #define PH(k) if (((PHMASK >> (k)) & 1) && lo <= (k) && (k) < hi) for (int rep_ = 0; rep_ < 1 + ((DUPMASK >> (k)) & 1); ++rep_)
; template <int DQK, bool BIAS>
; DI void attn_item(LAS unsigned char* lds, const AttItem it) {
;     ...
;     const int sr = tid >> 3, c8 = tid & 7;
;     const unsigned kgo = (unsigned)(sr * 2048 + c8 * 16), krgo = (unsigned)(sr * 128 + c8 * 16), vgo = (unsigned)((sr * it.vstride + 8 * c8) * 2);
;     const unsigned kl0 = (unsigned)(sr * KP + c8 * 16), vl0 = (unsigned)(KBYTES + sr * VP + c8 * 16);
;     u32x4 kreg[NKC], vreg[2];
;     const u32x4 zero4 = {0u, 0u, 0u, 0u};
;     ...
;     f32x16 oacc[4];
; #pragma unroll
;     for (int d = 0; d < 4; ++d)
; #pragma unroll
;         for (int i = 0; i < 16; ++i) oacc[d][i] = 0.f;
;     float m_run = NEGF, l_run = 0.f;
;     const int cq = it.cq0 + (wid >> 1);
;     const int kap = (l31 & 0x13) | ((l31 & 4) << 1) | ((l31 & 8) >> 1);
;     const unsigned kaoff = (unsigned)(kap * KP + h * 16), vaoff = (unsigned)(KBYTES + l31 * VP + h * 16);
; __global__ void __launch_bounds__(512) mk_fwd(Params p) {
;     ...
;     PH(7) {
;         const float scA = 0.08838834764831845f * LOG2E, scM = 0.07216878364870323f * LOG2E;
;         unsigned* qctr = (unsigned*)(ws + WS_BAR) + 3840; volatile LAS unsigned* qsh = bst + 2;
;         for (;;) {
;             __syncthreads();
;             if (tid == 0) *qsh = atomicAdd(qctr, 1u);
;             __syncthreads();
;             const int q = (int)*qsh;
;             if (q >= 2176) break;
.LBB0_1106:
	s_cmp_lt_i32 s24, 8
	s_cselect_b64 s[10:11], -1, 0
	s_and_b64 s[0:1], s[10:11], s[6:7]
	s_andn2_b64 vcc, exec, s[0:1]
	v_mbcnt_lo_u32_b32 v204, -1, 0
	s_cbranch_vccnz .LBB0_1278
	s_add_u32 s12, s22, 0x3f40ec00
	s_addc_u32 s13, s23, 0
	s_add_u32 s3, s22, 0x107c3000
	s_addc_u32 s58, s23, 0
	s_add_u32 s59, s22, 0x1c843000
	s_addc_u32 s60, s23, 0
	s_add_u32 s61, s22, 0x1d0c3000
	s_addc_u32 s62, s23, 0
	s_add_u32 s63, s22, 0x23a03000
	s_addc_u32 s64, s23, 0
	s_add_u32 s65, s22, 0x1d943000
	s_addc_u32 s66, s23, 0
	s_add_u32 s67, s22, 0x2c30b000
	s_addc_u32 s68, s23, 0
	s_add_u32 s69, s22, 0x2bb03000
	s_addc_u32 s70, s23, 0
	s_add_u32 s71, s22, 0x3838b000
	s_addc_u32 s72, s23, 0
	v_readlane_b32 s0, v244, 1
	s_add_u32 s73, s22, 0x14843000
	v_readlane_b32 s1, v244, 2
	s_addc_u32 s74, s23, 0
	s_load_dwordx2 s[14:15], s[0:1], 0x98
	s_add_u32 s75, s22, 0x18843000
	v_and_b32_e32 v2, 7, v184
	s_addc_u32 s76, s23, 0
	v_lshlrev_b32_e32 v3, 4, v2
	v_lshlrev_b32_e32 v206, 3, v2
	v_mul_u32_u24_e32 v2, 0x110, v187
	v_lshlrev_b32_e32 v5, 1, v184
	v_lshrrev_b32_e32 v6, 1, v184
	s_add_u32 s77, s22, 0x3438b000
	s_waitcnt lgkmcnt(0)
	v_bfe_u32 v1, v184, 5, 1
	v_and_b32_e32 v4, 19, v184
	v_and_b32_e32 v5, 8, v5
	v_and_b32_e32 v6, 4, v6
	v_add3_u32 v210, 0, v2, v3
	v_lshlrev_b32_e32 v2, 7, v187
	s_addc_u32 s78, s23, 0
	v_and_b32_e32 v189, 31, v184
	s_movk_i32 s0, 0x101
	v_mov_b32_e32 v0, 0
	s_add_i32 s79, 0, 0x20000
	v_lshlrev_b32_e32 v188, 3, v1
	v_or3_b32 v4, v4, v5, v6
	v_sub_u32_e32 v211, v210, v2
	s_add_i32 s80, 0, 0x207f8
	v_cmp_gt_u32_e64 s[6:7], s0, v184
	s_mov_b32 s17, 0
	v_lshl_add_u32 v205, v184, 2, s79
	v_lshl_or_b32 v190, v187, 11, v3
	v_lshlrev_b32_e32 v207, 4, v1
	v_mul_u32_u24_e32 v208, 0x90, v189
	v_mov_b32_e32 v191, v0
	v_mul_u32_u24_e32 v209, 0x110, v4
	v_lshlrev_b32_e32 v192, 2, v1
	v_or_b32_e32 v194, v2, v3
	v_mov_b32_e32 v195, v0
	v_mul_u32_u24_e32 v212, 0x190, v4
	v_lshl_add_u32 v213, v187, 8, v211
	v_or_b32_e32 v214, 64, v206
	s_movk_i32 s81, 0x87f
	s_movk_i32 s82, 0xff80
	v_lshlrev_b32_e32 v215, 2, v184
	s_mov_b32 s83, 0xf149f2ca
	v_mov_b32_e32 v216, s80
	v_lshlrev_b32_e32 v196, 1, v188
	v_mov_b32_e32 v217, 0x80
	v_mov_b32_e32 v218, 0xf149f2ca
	v_mbcnt_hi_u32_b32 v219, -1, v204
	s_and_saveexec_b64 s[94:95], s[90:91]
	s_cbranch_execz .Lq_pre_done
	v_mov_b32_e32 v233, 1
	v_mov_b32_e32 v234, 0
	global_atomic_add v232, v234, v233, s[12:13] sc0
.Lq_pre_done:
	s_or_b64 exec, exec, s[94:95]
	s_branch .LBB0_1110

; __global__ void __launch_bounds__(512) mk_fwd(Params p) {
;     ...
;         for (;;) {
;             __syncthreads();
;             if (tid == 0) *qsh = atomicAdd(qctr, 1u);
;             __syncthreads();
;             const int q = (int)*qsh;
;             if (q >= 2176) break;
.LBB0_1110:
	s_waitcnt vmcnt(0)
	s_barrier
	s_and_saveexec_b64 s[8:9], s[90:91]
	s_cbranch_execz .LBB0_1114
	v_mov_b32_e32 v2, s80
	v_mov_b32_e32 v235, v232
	v_mov_b32_e32 v233, 1
	v_mov_b32_e32 v234, 0
	ds_write_b32 v2, v235
	global_atomic_add v232, v234, v233, s[12:13] sc0
